# v64 (streamlined converter for the full-tile prologue matrices) padded with 6 s_nop so that all later code sits at v59's addresses mod 128
# speedup vs baseline: 1.0086x; 1.0071x over previous
; #define LAS __attribute__((address_space(3)))
; __device__ __forceinline__ void convert_mats(Frame& F, int m_lo, int m_hi, int gw, int NGW) {
;     LAS float* scr = (LAS float*)(F.lds + F.wave * 16384);
;     int it = gw, base = 0;
;     for (int mi = m_lo; mi < m_hi; ++mi) {
;         const MatI mt = kMats[mi]; const int cnt = (mt.Kp / 64) * (mt.Np / 64);
;         const float* src = in_ptr(F, mt.in_idx) + mt.src_off; const float* gain = mt.gain_idx >= 0 ? in_ptr(F, mt.gain_idx) + mt.gain_off : nullptr; bf16* dst = (bf16*)((unsigned char*)in_ptr(F, T_WS) + mt.dst_off);
;         while (it < base + cnt) {
;             f32x4 va[2][8], vb[2][8];
;             const int lim = base + cnt, i1 = it + NGW;
.Lcvp_m21_done:
	s_mov_b32 s22, s23
	s_waitcnt vmcnt(0)
	s_nop 0
	s_nop 0
	s_nop 0
	s_nop 0
	s_nop 0
	s_nop 0
	s_add_i32 s3, 0, 0x20520
	v_mov_b32_e32 v0, s3
	v_mbcnt_lo_u32_b32 v132, -1, 0
	v_mbcnt_hi_u32_b32 v132, -1, v132
	ds_read_b64 v[0:1], v0
	s_lshl_b32 s0, s96, 3
	s_add_i32 s44, s0, s80
	s_lshl_b32 s0, s80, 14
	v_ashrrev_i32_e32 v133, 3, v132
	s_waitcnt lgkmcnt(0)
	v_readfirstlane_b32 s38, v0
	v_lshlrev_b32_e32 v0, 2, v132
	v_and_b32_e32 v143, 28, v0
	v_and_b32_e32 v0, 7, v132
	s_add_i32 s0, s0, 0
	v_mul_u32_u24_e32 v3, 0x420, v0
	v_lshlrev_b32_e32 v4, 2, v133
	v_readfirstlane_b32 s39, v1
	v_lshl_add_u32 v1, v0, 4, s0
	v_add3_u32 v145, s0, v3, v4
	s_movk_i32 s0, 0x84
	v_lshlrev_b32_e32 v2, 3, v0
	v_mul_lo_u32 v3, v133, s0
	s_mov_b32 s49, 0
	s_lshl_b32 s46, s52, 3
	v_mov_b32_e32 v0, 0
	v_add_u32_e32 v147, 8, v133
	v_add_u32_e32 v149, 16, v133
	v_add_u32_e32 v151, 24, v133
	v_lshlrev_b32_e32 v134, 1, v2
	v_add_u32_e32 v153, v1, v3
	s_mov_b32 s20, s44
	s_mov_b32 s34, 0
	s_mov_b32 s33, 0
	s_branch .LBB0_14
